# EpiRes double-buffered row groups
# speedup vs baseline: 1.0029x; 1.0029x over previous
.LBB0_772:
	s_and_b64 vcc, exec, s[4:5]
	s_cbranch_vccz .LBB0_774
	s_load_dwordx2 s[4:5], s[0:1], 0x148
	s_lshl_b32 s38, s70, 2
	v_lshlrev_b32_e32 v128, 2, v172
	v_mov_b32_e32 v129, v169
	s_waitcnt lgkmcnt(0)
	s_add_u32 s30, s4, s38
	s_addc_u32 s31, s5, 0
	v_lshl_add_u64 v[130:131], s[30:31], 0, v[128:129]
	s_lshl_b64 s[30:31], s[24:25], 2
	v_lshl_add_u64 v[130:131], v[130:131], 0, s[30:31]
	v_add_u32_e32 v250, s54, v192
	v_ashrrev_i32_e32 v251, 31, v250
	v_lshlrev_b64 v[250:251], 13, v[250:251]
	v_lshl_add_u64 v[164:165], v[130:131], 0, v[250:251]
	global_load_dwordx4 v[132:135], v[164:165], off
	global_load_dwordx4 v[136:139], v[164:165], off offset:64
	global_load_dwordx4 v[140:143], v[164:165], off offset:512
	global_load_dwordx4 v[144:147], v[164:165], off offset:576
	v_add_u32_e32 v250, s54, v194
	v_ashrrev_i32_e32 v251, 31, v250
	v_lshlrev_b64 v[250:251], 13, v[250:251]
	v_lshl_add_u64 v[166:167], v[130:131], 0, v[250:251]
	global_load_dwordx4 v[148:151], v[166:167], off
	global_load_dwordx4 v[152:155], v[166:167], off offset:64
	global_load_dwordx4 v[156:159], v[166:167], off offset:512
	global_load_dwordx4 v[160:163], v[166:167], off offset:576
	v_add_u32_e32 v250, s54, v195
	v_ashrrev_i32_e32 v251, 31, v250
	v_lshlrev_b64 v[250:251], 13, v[250:251]
	v_lshl_add_u64 v[224:225], v[130:131], 0, v[250:251]
	global_load_dwordx4 v[204:207], v[224:225], off
	global_load_dwordx4 v[208:211], v[224:225], off offset:64
	global_load_dwordx4 v[212:215], v[224:225], off offset:512
	global_load_dwordx4 v[216:219], v[224:225], off offset:576
	v_add_u32_e32 v250, s54, v196
	v_ashrrev_i32_e32 v251, 31, v250
	v_lshlrev_b64 v[250:251], 13, v[250:251]
	v_lshl_add_u64 v[248:249], v[130:131], 0, v[250:251]
	global_load_dwordx4 v[220:223], v[248:249], off
	global_load_dwordx4 v[232:235], v[248:249], off offset:64
	global_load_dwordx4 v[240:243], v[248:249], off offset:512
	global_load_dwordx4 v[244:247], v[248:249], off offset:576
	s_waitcnt vmcnt(8)
	v_pk_add_f32 v[132:133], v[124:125], v[132:133]
	v_pk_add_f32 v[134:135], v[126:127], v[134:135]
	global_store_dwordx4 v[164:165], v[132:135], off
	v_pk_add_f32 v[136:137], v[120:121], v[136:137]
	v_pk_add_f32 v[138:139], v[122:123], v[138:139]
	global_store_dwordx4 v[164:165], v[136:139], off offset:64
	v_pk_add_f32 v[140:141], v[116:117], v[140:141]
	v_pk_add_f32 v[142:143], v[118:119], v[142:143]
	global_store_dwordx4 v[164:165], v[140:143], off offset:512
	v_pk_add_f32 v[144:145], v[112:113], v[144:145]
	v_pk_add_f32 v[146:147], v[114:115], v[146:147]
	global_store_dwordx4 v[164:165], v[144:147], off offset:576
	v_pk_add_f32 v[148:149], v[108:109], v[148:149]
	v_pk_add_f32 v[150:151], v[110:111], v[150:151]
	global_store_dwordx4 v[166:167], v[148:151], off
	v_pk_add_f32 v[152:153], v[104:105], v[152:153]
	v_pk_add_f32 v[154:155], v[106:107], v[154:155]
	global_store_dwordx4 v[166:167], v[152:155], off offset:64
	v_pk_add_f32 v[156:157], v[100:101], v[156:157]
	v_pk_add_f32 v[158:159], v[102:103], v[158:159]
	global_store_dwordx4 v[166:167], v[156:159], off offset:512
	v_pk_add_f32 v[160:161], v[96:97], v[160:161]
	v_pk_add_f32 v[162:163], v[98:99], v[162:163]
	global_store_dwordx4 v[166:167], v[160:163], off offset:576
	s_nop 1
	v_add_u32_e32 v250, s54, v197
	v_ashrrev_i32_e32 v251, 31, v250
	v_lshlrev_b64 v[250:251], 13, v[250:251]
	v_lshl_add_u64 v[164:165], v[130:131], 0, v[250:251]
	global_load_dwordx4 v[132:135], v[164:165], off
	global_load_dwordx4 v[136:139], v[164:165], off offset:64
	global_load_dwordx4 v[140:143], v[164:165], off offset:512
	global_load_dwordx4 v[144:147], v[164:165], off offset:576
	v_add_u32_e32 v250, s54, v198
	v_ashrrev_i32_e32 v251, 31, v250
	v_lshlrev_b64 v[250:251], 13, v[250:251]
	v_lshl_add_u64 v[166:167], v[130:131], 0, v[250:251]
	global_load_dwordx4 v[148:151], v[166:167], off
	global_load_dwordx4 v[152:155], v[166:167], off offset:64
	global_load_dwordx4 v[156:159], v[166:167], off offset:512
	global_load_dwordx4 v[160:163], v[166:167], off offset:576
	s_waitcnt vmcnt(16)
	v_pk_add_f32 v[204:205], v[92:93], v[204:205]
	v_pk_add_f32 v[206:207], v[94:95], v[206:207]
	global_store_dwordx4 v[224:225], v[204:207], off
	v_pk_add_f32 v[208:209], v[88:89], v[208:209]
	v_pk_add_f32 v[210:211], v[90:91], v[210:211]
	global_store_dwordx4 v[224:225], v[208:211], off offset:64
	v_pk_add_f32 v[212:213], v[84:85], v[212:213]
	v_pk_add_f32 v[214:215], v[86:87], v[214:215]
	global_store_dwordx4 v[224:225], v[212:215], off offset:512
	v_pk_add_f32 v[216:217], v[80:81], v[216:217]
	v_pk_add_f32 v[218:219], v[82:83], v[218:219]
	global_store_dwordx4 v[224:225], v[216:219], off offset:576
	v_pk_add_f32 v[220:221], v[76:77], v[220:221]
	v_pk_add_f32 v[222:223], v[78:79], v[222:223]
	global_store_dwordx4 v[248:249], v[220:223], off
	v_pk_add_f32 v[232:233], v[72:73], v[232:233]
	v_pk_add_f32 v[234:235], v[74:75], v[234:235]
	global_store_dwordx4 v[248:249], v[232:235], off offset:64
	v_pk_add_f32 v[240:241], v[68:69], v[240:241]
	v_pk_add_f32 v[242:243], v[70:71], v[242:243]
	global_store_dwordx4 v[248:249], v[240:243], off offset:512
	v_pk_add_f32 v[244:245], v[64:65], v[244:245]
	v_pk_add_f32 v[246:247], v[66:67], v[246:247]
	global_store_dwordx4 v[248:249], v[244:247], off offset:576
	s_nop 1
	v_add_u32_e32 v250, s54, v199
	v_ashrrev_i32_e32 v251, 31, v250
	v_lshlrev_b64 v[250:251], 13, v[250:251]
	v_lshl_add_u64 v[224:225], v[130:131], 0, v[250:251]
	global_load_dwordx4 v[204:207], v[224:225], off
	global_load_dwordx4 v[208:211], v[224:225], off offset:64
	global_load_dwordx4 v[212:215], v[224:225], off offset:512
	global_load_dwordx4 v[216:219], v[224:225], off offset:576
	v_add_u32_e32 v250, s54, v200
	v_ashrrev_i32_e32 v251, 31, v250
	v_lshlrev_b64 v[250:251], 13, v[250:251]
	v_lshl_add_u64 v[248:249], v[130:131], 0, v[250:251]
	global_load_dwordx4 v[220:223], v[248:249], off
	global_load_dwordx4 v[232:235], v[248:249], off offset:64
	global_load_dwordx4 v[240:243], v[248:249], off offset:512
	global_load_dwordx4 v[244:247], v[248:249], off offset:576
	s_waitcnt vmcnt(16)
	v_pk_add_f32 v[132:133], v[60:61], v[132:133]
	v_pk_add_f32 v[134:135], v[62:63], v[134:135]
	global_store_dwordx4 v[164:165], v[132:135], off
	v_pk_add_f32 v[136:137], v[56:57], v[136:137]
	v_pk_add_f32 v[138:139], v[58:59], v[138:139]
	global_store_dwordx4 v[164:165], v[136:139], off offset:64
	v_pk_add_f32 v[140:141], v[52:53], v[140:141]
	v_pk_add_f32 v[142:143], v[54:55], v[142:143]
	global_store_dwordx4 v[164:165], v[140:143], off offset:512
	v_pk_add_f32 v[144:145], v[48:49], v[144:145]
	v_pk_add_f32 v[146:147], v[50:51], v[146:147]
	global_store_dwordx4 v[164:165], v[144:147], off offset:576
	v_pk_add_f32 v[148:149], v[44:45], v[148:149]
	v_pk_add_f32 v[150:151], v[46:47], v[150:151]
	global_store_dwordx4 v[166:167], v[148:151], off
	v_pk_add_f32 v[152:153], v[40:41], v[152:153]
	v_pk_add_f32 v[154:155], v[42:43], v[154:155]
	global_store_dwordx4 v[166:167], v[152:155], off offset:64
	v_pk_add_f32 v[156:157], v[36:37], v[156:157]
	v_pk_add_f32 v[158:159], v[38:39], v[158:159]
	global_store_dwordx4 v[166:167], v[156:159], off offset:512
	v_pk_add_f32 v[160:161], v[32:33], v[160:161]
	v_pk_add_f32 v[162:163], v[34:35], v[162:163]
	global_store_dwordx4 v[166:167], v[160:163], off offset:576
	s_waitcnt vmcnt(8)
	v_pk_add_f32 v[204:205], v[28:29], v[204:205]
	v_pk_add_f32 v[206:207], v[30:31], v[206:207]
	global_store_dwordx4 v[224:225], v[204:207], off
	v_pk_add_f32 v[208:209], v[24:25], v[208:209]
	v_pk_add_f32 v[210:211], v[26:27], v[210:211]
	global_store_dwordx4 v[224:225], v[208:211], off offset:64
	v_pk_add_f32 v[212:213], v[20:21], v[212:213]
	v_pk_add_f32 v[214:215], v[22:23], v[214:215]
	global_store_dwordx4 v[224:225], v[212:215], off offset:512
	v_pk_add_f32 v[216:217], v[16:17], v[216:217]
	v_pk_add_f32 v[218:219], v[18:19], v[218:219]
	global_store_dwordx4 v[224:225], v[216:219], off offset:576
	v_pk_add_f32 v[220:221], v[12:13], v[220:221]
	v_pk_add_f32 v[222:223], v[14:15], v[222:223]
	global_store_dwordx4 v[248:249], v[220:223], off
	v_pk_add_f32 v[232:233], v[8:9], v[232:233]
	v_pk_add_f32 v[234:235], v[10:11], v[234:235]
	global_store_dwordx4 v[248:249], v[232:235], off offset:64
	v_pk_add_f32 v[240:241], v[4:5], v[240:241]
	v_pk_add_f32 v[242:243], v[6:7], v[242:243]
	global_store_dwordx4 v[248:249], v[240:243], off offset:512
	v_pk_add_f32 v[244:245], v[0:1], v[244:245]
	v_pk_add_f32 v[246:247], v[2:3], v[246:247]
	global_store_dwordx4 v[248:249], v[244:247], off offset:576
